# k16 + HGRN A/C: the two serialized lb_of gate round trips per item/direction merged into one (dwordx2 per array, one wait)
# speedup vs baseline: 1.0037x; 1.0037x over previous
; __device__ __forceinline__ float sigmoidf_(float x) { return __builtin_amdgcn_rcpf(1.0f + __builtin_amdgcn_exp2f(x * -1.4426950408889634f)); }
; __device__ __forceinline__ float lb_of(const Frame& F, int l, int dir, int ch) {
;     if (l == 0) return 0.f;
;     const float x0 = F.a->in[8][(size_t)(dir * DEPTH + 0) * D + ch], x1 = F.a->in[8][(size_t)(dir * DEPTH + 1) * D + ch];
;     return sigmoidf_(x1 - x0);
; }
; template <int DIR>
; __device__ __forceinline__ void hgrn_a_item(const Frame& F, int l, int it, int h, int row0, unsigned (&rf)[8], unsigned (&rv)[8], bool pre, int itn  ) {
;     ...
;     const f32x2 lb = {hg::lb_of(F, l, DIR, h * 128 + 2 * F.lane), hg::lb_of(F, l, DIR, h * 128 + 2 * F.lane + 1)};
.LBB0_624:
	s_xor_b64 s[26:27], s[0:1], -1
	s_and_b32 s11, s3, 7
	s_add_i32 s4, s2, s83
	s_cmpk_gt_i32 s4, 0x41f
	s_cselect_b64 s[68:69], -1, 0
	s_cmpk_lt_i32 s4, 0x420
	s_cselect_b32 s5, s4, -1
	s_bitcmp1_b32 s7, 0
	s_cselect_b64 s[0:1], -1, 0
	v_lshl_add_u32 v36, s11, 7, v71
	s_and_b64 vcc, exec, s[0:1]
	s_cbranch_vccz .LBB0_635
	v_readlane_b32 s16, v255, 29
	v_readlane_b32 s17, v255, 30
	v_mov_b32_e32 v3, 0
	s_andn2_b64 vcc, exec, s[16:17]
	v_cndmask_b32_e64 v0, 0, 1, s[16:17]
	v_cmp_ne_u32_e64 s[0:1], 1, v0
	v_mov_b32_e32 v2, 0
	s_cbranch_vccnz .LBB0_627
	v_ashrrev_i32_e32 v37, 31, v36
	v_readlane_b32 s16, v251, 16
	s_waitcnt lgkmcnt(1)
	v_lshlrev_b64 v[4:5], 2, v[36:37]
	v_readlane_b32 s17, v251, 17
	s_waitcnt lgkmcnt(0)
	s_nop 0
	v_lshl_add_u64 v[6:7], s[16:17], 0, v[4:5]
	v_readlane_b32 s16, v251, 18
	v_readlane_b32 s17, v251, 19
	global_load_dwordx2 v[6:7], v[6:7], off
	s_nop 0
	v_lshl_add_u64 v[4:5], s[16:17], 0, v[4:5]
	global_load_dwordx2 v[4:5], v[4:5], off
	s_waitcnt vmcnt(0)
	v_sub_f32_e32 v0, v4, v6
	v_sub_f32_e32 v3, v5, v7
	v_mul_f32_e32 v0, 0xbfb8aa3b, v0
	v_mul_f32_e32 v3, 0xbfb8aa3b, v3
	v_exp_f32_e32 v0, v0
	v_exp_f32_e32 v3, v3
	s_nop 0
	v_add_f32_e32 v0, 1.0, v0
	v_add_f32_e32 v3, 1.0, v3
	v_rcp_f32_e32 v2, v0
	v_rcp_f32_e32 v3, v3
	s_branch .LBB0_629

; __device__ __forceinline__ float sigmoidf_(float x) { return __builtin_amdgcn_rcpf(1.0f + __builtin_amdgcn_exp2f(x * -1.4426950408889634f)); }
; __device__ __forceinline__ float lb_of(const Frame& F, int l, int dir, int ch) {
;     if (l == 0) return 0.f;
;     const float x0 = F.a->in[8][(size_t)(dir * DEPTH + 0) * D + ch], x1 = F.a->in[8][(size_t)(dir * DEPTH + 1) * D + ch];
;     return sigmoidf_(x1 - x0);
; }
; template <int DIR>
; __device__ __forceinline__ void hgrn_a_item(const Frame& F, int l, int it, int h, int row0, unsigned (&rf)[8], unsigned (&rv)[8], bool pre, int itn  ) {
;     ...
;     const f32x2 lb = {hg::lb_of(F, l, DIR, h * 128 + 2 * F.lane), hg::lb_of(F, l, DIR, h * 128 + 2 * F.lane + 1)};
.LBB0_648:
	v_readlane_b32 s16, v251, 33
	s_waitcnt lgkmcnt(1)
	v_lshlrev_b64 v[4:5], 2, v[36:37]
	v_readlane_b32 s17, v251, 34
	s_waitcnt lgkmcnt(0)
	v_lshl_add_u64 v[6:7], s[36:37], 0, v[4:5]
	global_load_dwordx2 v[6:7], v[6:7], off
	v_lshl_add_u64 v[4:5], s[16:17], 0, v[4:5]
	global_load_dwordx2 v[4:5], v[4:5], off
	s_waitcnt vmcnt(0)
	v_sub_f32_e32 v0, v4, v6
	v_sub_f32_e32 v3, v5, v7
	v_mul_f32_e32 v0, 0xbfb8aa3b, v0
	v_mul_f32_e32 v3, 0xbfb8aa3b, v3
	v_exp_f32_e32 v0, v0
	v_exp_f32_e32 v3, v3
	s_nop 0
	v_add_f32_e32 v0, 1.0, v0
	v_add_f32_e32 v3, 1.0, v3
	v_rcp_f32_e32 v2, v0
	v_rcp_f32_e32 v3, v3
	s_andn2_b64 vcc, exec, s[26:27]
	s_cbranch_vccz .LBB0_640
	s_branch .LBB0_641

; __device__ __forceinline__ float sigmoidf_(float x) { return __builtin_amdgcn_rcpf(1.0f + __builtin_amdgcn_exp2f(x * -1.4426950408889634f)); }
; __device__ __forceinline__ float lb_of(const Frame& F, int l, int dir, int ch) {
;     if (l == 0) return 0.f;
;     const float x0 = F.a->in[8][(size_t)(dir * DEPTH + 0) * D + ch], x1 = F.a->in[8][(size_t)(dir * DEPTH + 1) * D + ch];
;     return sigmoidf_(x1 - x0);
; }
; template <int DIR>
; __device__ __forceinline__ void hgrn_c_dir(const Frame& F, int l, int it_lat  , int h, int row0, bf16_t* QV, unsigned* ofs  , bool dry,
;                                            unsigned (&rf)[8], unsigned (&rq)[8], unsigned (&rv)[8], bool pre, int itn  ) {
;     ...
;     const f32x2 lb = {hg::lb_of(F, l, DIR, h * 128 + 2 * lane), hg::lb_of(F, l, DIR, h * 128 + 2 * lane + 1)};
.LBB0_722:
	v_readlane_b32 s38, v251, 33
	v_lshlrev_b64 v[2:3], 2, v[86:87]
	v_readlane_b32 s39, v251, 34
	s_waitcnt lgkmcnt(1)
	v_lshl_add_u64 v[4:5], s[36:37], 0, v[2:3]
	global_load_dwordx2 v[4:5], v[4:5], off
	v_lshl_add_u64 v[2:3], s[38:39], 0, v[2:3]
	global_load_dwordx2 v[2:3], v[2:3], off
	v_or_b32_e32 v88, 1, v86
	v_ashrrev_i32_e32 v89, 31, v88
	s_waitcnt vmcnt(0)
	v_sub_f32_e32 v0, v2, v4
	v_sub_f32_e32 v2, v3, v5
	v_mul_f32_e32 v0, 0xbfb8aa3b, v0
	v_mul_f32_e32 v2, 0xbfb8aa3b, v2
	v_exp_f32_e32 v0, v0
	v_exp_f32_e32 v2, v2
	s_nop 0
	v_add_f32_e32 v0, 1.0, v0
	v_add_f32_e32 v2, 1.0, v2
	v_rcp_f32_e32 v48, v0
	v_rcp_f32_e32 v49, v2
	v_cndmask_b32_e64 v0, 0, 1, s[26:27]
	v_cmp_ne_u32_e64 s[76:77], 1, v0
	s_andn2_b64 vcc, exec, s[26:27]
	s_cbranch_vccz .LBB0_721
	s_branch .LBB0_724

; __device__ __forceinline__ float sigmoidf_(float x) { return __builtin_amdgcn_rcpf(1.0f + __builtin_amdgcn_exp2f(x * -1.4426950408889634f)); }
; __device__ __forceinline__ float lb_of(const Frame& F, int l, int dir, int ch) {
;     if (l == 0) return 0.f;
;     const float x0 = F.a->in[8][(size_t)(dir * DEPTH + 0) * D + ch], x1 = F.a->in[8][(size_t)(dir * DEPTH + 1) * D + ch];
;     return sigmoidf_(x1 - x0);
; }
; template <int DIR>
; __device__ __forceinline__ void hgrn_c_dir(const Frame& F, int l, int it_lat  , int h, int row0, bf16_t* QV, unsigned* ofs  , bool dry,
;                                            unsigned (&rf)[8], unsigned (&rq)[8], unsigned (&rv)[8], bool pre, int itn  ) {
;     ...
;     const f32x2 lb = {hg::lb_of(F, l, DIR, h * 128 + 2 * lane), hg::lb_of(F, l, DIR, h * 128 + 2 * lane + 1)};
.LBB0_781:
	v_readlane_b32 s2, v251, 16
	v_lshlrev_b64 v[2:3], 2, v[86:87]
	v_readlane_b32 s3, v251, 17
	s_nop 1
	v_lshl_add_u64 v[4:5], s[2:3], 0, v[2:3]
	v_readlane_b32 s2, v251, 18
	v_readlane_b32 s3, v251, 19
	global_load_dwordx2 v[4:5], v[4:5], off
	s_nop 0
	v_lshl_add_u64 v[2:3], s[2:3], 0, v[2:3]
	global_load_dwordx2 v[2:3], v[2:3], off
	s_waitcnt vmcnt(0)
	v_sub_f32_e32 v0, v2, v4
	v_sub_f32_e32 v2, v3, v5
	v_mul_f32_e32 v0, 0xbfb8aa3b, v0
	v_mul_f32_e32 v2, 0xbfb8aa3b, v2
	v_exp_f32_e32 v0, v0
	v_exp_f32_e32 v2, v2
	s_nop 0
	v_add_f32_e32 v0, 1.0, v0
	v_add_f32_e32 v2, 1.0, v2
	v_rcp_f32_e32 v48, v0
	v_rcp_f32_e32 v49, v2
	s_and_b64 vcc, exec, s[76:77]
	s_cbranch_vccz .LBB0_780
	s_branch .LBB0_783
